# opt7
# speedup vs baseline: 1.0503x; 1.0084x over previous
; __device__ __forceinline__ void gemm_phase(const Ctx& cx, const GemmArgs& g_, char* shm) {
;     ...
;             if (g.epi == EPI_PROJ || g.epi == EPI_RELU2) { a[0] *= rs; a[1] *= rs; a[2] *= rs; a[3] *= rs; }
;             if (g.epi == EPI_PROJ) {
;               if (n0 >= C_GLAX) {
;                 const int i = n0 - C_GLAX;
;                 const float4 b4 = *(const float4*)(g.hin + i);
;                 float xs[4] = {a[0] + b4.x, a[1] + b4.y, a[2] + b4.z, a[3] + b4.w};
; #pragma unroll
;                 for (int j = 0; j < 4; ++j)
;                   xs[j] = (fminf(xs[j], 0.f) - __logf(1.0f + __expf(-fabsf(xs[j])))) * (1.0f / 16.0f);
;                 *(float4*)(g.f32buf + (size_t)tok * 1024 + i) = make_float4(xs[0], xs[1], xs[2], xs[3]);
;               } else {
;                 float o0 = a[0], o1 = a[1], o2 = a[2], o3 = a[3];
;                 const bool r128 = (n0 >= C_DSAQ && n0 < C_HGQ) || (n0 >= C_DSAK && n0 < C_DSAV);
;                 const bool r64 = (n0 >= C_IDXQ && n0 < C_GLAA);
;                 if (r128 || r64) {
;                   float4 cs;
;                   float sc;
;                   if (r128) {
;                     cs = *(const float4*)(g.w + ((size_t)tok * 64 + ((n0 & 127) >> 1)) * 2);
;                     sc = (n0 < C_HGQ) ? 0.08838834764831845f : 1.0f;
;                   } else {
;                     cs = *(const float4*)(g.hout + ((size_t)tok * 32 + ((n0 & 63) >> 1)) * 2);
;                     sc = (n0 < C_IDXK) ? 0.125f : 1.0f;
;                   }
;                   o0 = (a[0] * cs.x - a[1] * cs.y) * sc; o1 = (a[1] * cs.x + a[0] * cs.y) * sc;
;                   o2 = (a[2] * cs.z - a[3] * cs.w) * sc; o3 = (a[3] * cs.z + a[2] * cs.w) * sc;
;                 }
;                 uint2 o; o.x = pack2(o0, o1); o.y = pack2(o2, o3);
;                 EMIT_BF16(g.ldo, o);
;               }
;             } else if (g.epi == EPI_RELU2) {
;               float r0 = fmaxf(a[0], 0.f), r1 = fmaxf(a[1], 0.f), r2 = fmaxf(a[2], 0.f), r3 = fmaxf(a[3], 0.f);
;               uint2 o; o.x = pack2(r0 * r0, r1 * r1); o.y = pack2(r2 * r2, r3 * r3);
;               EMIT_BF16(g.ldo, o);
;             } else if (g.epi == EPI_RES) {
.LBB0_248:
	s_cmp_eq_u32 s38, 5
	s_cbranch_scc1 .Lmy_fast_relu
	s_cmp_lt_u32 s38, 4
	s_cselect_b32 s0, 1, 0
	s_cmp_gt_u32 s38, 0
	s_cselect_b32 s3, 1, 0
	s_and_b32 s0, s0, s3
	s_cmp_lg_u32 s0, 0
	s_cbranch_scc1 .Lmy_fast_br
	s_cmp_eq_u32 s38, 4
	s_cbranch_scc1 .Lmy_fast_res
	s_cmp_lg_u32 s38, 0
	s_cbranch_scc1 .Lmy_slow_epi
	s_cmpk_lt_u32 s2, 0x1800
	s_cbranch_scc1 .Lmy_fast_proj
	s_cmpk_lt_u32 s2, 0x2000
	s_cbranch_scc1 .Lmy_slow_epi
	s_cmpk_lt_u32 s2, 0x5800
	s_cbranch_scc1 .Lmy_fast_proj
	s_branch .Lmy_slow_epi

; __device__ __forceinline__ void gemm_phase(const Ctx& cx, const GemmArgs& g_, char* shm) {
;     ...
;             } else if (g.epi == EPI_RES) {
;               const float4 hv = *(const float4*)(g.hin + (size_t)tok * DM + n0);
;               const float h0 = hv.x + a[0], h1 = hv.y + a[1], h2 = hv.z + a[2], h3 = hv.w + a[3];
;               *(float4*)(g.hout + (size_t)tok * DM + n0) = make_float4(h0, h1, h2, h3);
;               if (g.w != nullptr) {
;                 const float4 nw = *(const float4*)(g.w + n0);
;                 uint2 o; o.x = pack2(h0 * nw.x, h1 * nw.y); o.y = pack2(h2 * nw.z, h3 * nw.w);
;                 EMIT_BF16(DM, o);
;                 ssq += h0 * h0 + h1 * h1 + h2 * h2 + h3 * h3;
;               }
.Lmy_fast_res:
	v_or_b32_e32 v194, s4, v168
	v_ashrrev_i32_e32 v195, 31, v194
	v_add_u32_e32 v186, s2, v169
	v_add_u32_e32 v188, v186, v170
	v_ashrrev_i32_e32 v189, 31, v188
	v_add_u32_e32 v186, v186, v0
	v_ashrrev_i32_e32 v187, 31, v186
	v_lshlrev_b64 v[184:185], 12, v[194:195]
	v_lshl_add_u64 v[184:185], s[20:21], 0, v[184:185]
	v_lshl_add_u64 v[184:185], v[188:189], 1, v[184:185]
	v_and_b32_e32 v192, 8, v168
	v_cmp_ne_u32_e32 vcc, 0, v192
	v_mov_b32_e32 v193, 0xffff8040
	s_nop 1
	v_cndmask_b32_e32 v192, 0, v193, vcc
	v_cndmask_b32_e64 v193, 0, -1, vcc
	v_lshl_add_u64 v[184:185], v[184:185], 0, v[192:193]
	v_lshlrev_b64 v[192:193], 13, v[194:195]
	v_lshl_add_u64 v[240:241], s[26:27], 0, v[192:193]
	v_lshl_add_u64 v[242:243], s[28:29], 0, v[192:193]
	v_lshl_add_u64 v[240:241], v[186:187], 2, v[240:241]
	v_lshl_add_u64 v[242:243], v[186:187], 2, v[242:243]
	v_lshl_add_u64 v[244:245], v[186:187], 2, s[30:31]
	v_lshl_add_u64 v[246:247], v[194:195], 2, s[24:25]
	s_mov_b32 s6, 0x8000
	s_mov_b32 s7, 0
	s_mov_b32 s8, 0x10000
	s_mov_b32 s9, 0
	s_mov_b32 s10, 0x80000
	s_mov_b32 s11, 0
	s_mov_b32 s2, 0x20000
	s_mov_b32 s3, 0
	s_mov_b32 s4, 0x100000
	s_mov_b32 s5, 0
	v_mov_b32_e32 v188, v184
	v_mov_b32_e32 v189, v185
	v_lshl_add_u64 v[190:191], v[188:189], 0, s[6:7]
	v_mov_b32_e32 v236, v240
	v_mov_b32_e32 v237, v241
	v_mov_b32_e32 v238, v242
	v_mov_b32_e32 v239, v243
	v_mov_b32_e32 v232, 0
	global_load_dwordx4 v[192:195], v[236:237], off offset:0
	global_load_dwordx4 v[196:199], v[236:237], off offset:64
	global_load_dwordx4 v[200:203], v[236:237], off offset:128
	global_load_dwordx4 v[204:207], v[236:237], off offset:192
	s_and_b64 vcc, exec, s[42:43]
	s_cbranch_vccz .Lmy_res_now_ld_0_0
	global_load_dwordx4 v[208:211], v[244:245], off offset:0
	global_load_dwordx4 v[212:215], v[244:245], off offset:64
	global_load_dwordx4 v[216:219], v[244:245], off offset:128
	global_load_dwordx4 v[220:223], v[244:245], off offset:192
.Lmy_res_now_ld_0_0:
	s_waitcnt vmcnt(0)
	v_pk_add_f32 v[128:129], v[128:129], v[192:193]
	v_pk_add_f32 v[130:131], v[130:131], v[194:195]
	global_store_dwordx4 v[238:239], v[128:131], off offset:0
	v_pk_add_f32 v[124:125], v[124:125], v[196:197]
	v_pk_add_f32 v[126:127], v[126:127], v[198:199]
	global_store_dwordx4 v[238:239], v[124:127], off offset:64
	v_pk_add_f32 v[120:121], v[120:121], v[200:201]
	v_pk_add_f32 v[122:123], v[122:123], v[202:203]
	global_store_dwordx4 v[238:239], v[120:123], off offset:128
	v_pk_add_f32 v[116:117], v[116:117], v[204:205]
	v_pk_add_f32 v[118:119], v[118:119], v[206:207]
	global_store_dwordx4 v[238:239], v[116:119], off offset:192
	s_and_b64 vcc, exec, s[42:43]
	s_cbranch_vccz .Lmy_res_now_0_0
	v_pk_mul_f32 v[234:235], v[130:131], v[210:211]
	s_nop 0
	v_cvt_pk_bf16_f32 v225, v234, v235
	v_pk_mul_f32 v[234:235], v[128:129], v[208:209]
	v_pk_mul_f32 v[208:209], v[128:129], v[128:129]
	v_pk_mul_f32 v[210:211], v[130:131], v[130:131]
	v_add_f32_e32 v233, v208, v209
	v_add_f32_e32 v233, v233, v210
	v_cvt_pk_bf16_f32 v224, v234, v235
	v_add_f32_e32 v233, v233, v211
	v_add_f32_e32 v232, v232, v233
	v_pk_mul_f32 v[234:235], v[126:127], v[214:215]
	s_nop 0
	v_cvt_pk_bf16_f32 v227, v234, v235
	v_pk_mul_f32 v[234:235], v[124:125], v[212:213]
	v_pk_mul_f32 v[212:213], v[124:125], v[124:125]
	v_pk_mul_f32 v[214:215], v[126:127], v[126:127]
	v_add_f32_e32 v233, v212, v213
	v_add_f32_e32 v233, v233, v214
	v_cvt_pk_bf16_f32 v226, v234, v235
	v_add_f32_e32 v233, v233, v215
	v_add_f32_e32 v232, v232, v233
	s_nop 1
	v_permlane16_swap_b32_e32 v224, v226
	v_permlane16_swap_b32_e32 v225, v227
	v_pk_mul_f32 v[234:235], v[122:123], v[218:219]
	s_nop 0
	v_cvt_pk_bf16_f32 v229, v234, v235
	v_pk_mul_f32 v[234:235], v[120:121], v[216:217]
	v_pk_mul_f32 v[216:217], v[120:121], v[120:121]
	v_pk_mul_f32 v[218:219], v[122:123], v[122:123]
	v_add_f32_e32 v233, v216, v217
	v_add_f32_e32 v233, v233, v218
	v_cvt_pk_bf16_f32 v228, v234, v235
	v_add_f32_e32 v233, v233, v219
	v_add_f32_e32 v232, v232, v233
	v_pk_mul_f32 v[234:235], v[118:119], v[222:223]
	s_nop 0
	v_cvt_pk_bf16_f32 v231, v234, v235
	v_pk_mul_f32 v[234:235], v[116:117], v[220:221]
	v_pk_mul_f32 v[220:221], v[116:117], v[116:117]
	v_pk_mul_f32 v[222:223], v[118:119], v[118:119]
	v_add_f32_e32 v233, v220, v221
	v_add_f32_e32 v233, v233, v222
	v_cvt_pk_bf16_f32 v230, v234, v235
	v_add_f32_e32 v233, v233, v223
	v_add_f32_e32 v232, v232, v233
	s_nop 1
	v_permlane16_swap_b32_e32 v228, v230
	v_permlane16_swap_b32_e32 v229, v231
	v_mov_b32_e32 v192, v228
	v_mov_b32_e32 v193, v229
	v_mov_b32_e32 v194, v230
	v_mov_b32_e32 v195, v231
	v_mov_b32_dpp v228, v224 row_ror:8 row_mask:0xf bank_mask:0x3
	v_mov_b32_dpp v229, v225 row_ror:8 row_mask:0xf bank_mask:0x3
	v_mov_b32_dpp v230, v226 row_ror:8 row_mask:0xf bank_mask:0x3
	v_mov_b32_dpp v231, v227 row_ror:8 row_mask:0xf bank_mask:0x3
	v_mov_b32_dpp v224, v192 row_ror:8 row_mask:0xf bank_mask:0xc
	v_mov_b32_dpp v225, v193 row_ror:8 row_mask:0xf bank_mask:0xc
	v_mov_b32_dpp v226, v194 row_ror:8 row_mask:0xf bank_mask:0xc
	v_mov_b32_dpp v227, v195 row_ror:8 row_mask:0xf bank_mask:0xc
	global_store_dwordx4 v[188:189], v[224:227], off offset:32
	global_store_dwordx4 v[190:191], v[228:231], off offset:32
	s_nop 1
.Lmy_res_now_0_0:
	global_load_dwordx4 v[192:195], v[236:237], off offset:512
	global_load_dwordx4 v[196:199], v[236:237], off offset:576
	global_load_dwordx4 v[200:203], v[236:237], off offset:640
	global_load_dwordx4 v[204:207], v[236:237], off offset:704
	s_and_b64 vcc, exec, s[42:43]
	s_cbranch_vccz .Lmy_res_now_ld_0_1
	global_load_dwordx4 v[208:211], v[244:245], off offset:512
	global_load_dwordx4 v[212:215], v[244:245], off offset:576
	global_load_dwordx4 v[216:219], v[244:245], off offset:640
	global_load_dwordx4 v[220:223], v[244:245], off offset:704
; __device__ __forceinline__ void gemm_phase(const Ctx& cx, const GemmArgs& g_, char* shm) {
;     ...
;             } else if (g.epi == EPI_RES) {
;               const float4 hv = *(const float4*)(g.hin + (size_t)tok * DM + n0);
;               const float h0 = hv.x + a[0], h1 = hv.y + a[1], h2 = hv.z + a[2], h3 = hv.w + a[3];
;               *(float4*)(g.hout + (size_t)tok * DM + n0) = make_float4(h0, h1, h2, h3);
;               if (g.w != nullptr) {
;                 const float4 nw = *(const float4*)(g.w + n0);
;                 uint2 o; o.x = pack2(h0 * nw.x, h1 * nw.y); o.y = pack2(h2 * nw.z, h3 * nw.w);
;                 EMIT_BF16(DM, o);
;                 ssq += h0 * h0 + h1 * h1 + h2 * h2 + h3 * h3;
;               }
;     ...
;         if (g.epi == EPI_RES && g.w != nullptr) {
;           float v2 = ssq;
;           v2 += shx(lane, v2, 16);
;           v2 += shx(lane, v2, 32);
;           if (fq == 0) __hip_atomic_fetch_add(g.f32buf + tok, v2, __ATOMIC_RELAXED, __HIP_MEMORY_SCOPE_AGENT);
;         }
.Lmy_res_now_ld_0_1:
	s_waitcnt vmcnt(0)
	v_pk_add_f32 v[112:113], v[112:113], v[192:193]
	v_pk_add_f32 v[114:115], v[114:115], v[194:195]
	global_store_dwordx4 v[238:239], v[112:115], off offset:512
	v_pk_add_f32 v[108:109], v[108:109], v[196:197]
	v_pk_add_f32 v[110:111], v[110:111], v[198:199]
	global_store_dwordx4 v[238:239], v[108:111], off offset:576
	v_pk_add_f32 v[104:105], v[104:105], v[200:201]
	v_pk_add_f32 v[106:107], v[106:107], v[202:203]
	global_store_dwordx4 v[238:239], v[104:107], off offset:640
	v_pk_add_f32 v[100:101], v[100:101], v[204:205]
	v_pk_add_f32 v[102:103], v[102:103], v[206:207]
	global_store_dwordx4 v[238:239], v[100:103], off offset:704
	s_and_b64 vcc, exec, s[42:43]
	s_cbranch_vccz .Lmy_res_now_0_1
	v_pk_mul_f32 v[234:235], v[114:115], v[210:211]
	s_nop 0
	v_cvt_pk_bf16_f32 v225, v234, v235
	v_pk_mul_f32 v[234:235], v[112:113], v[208:209]
	v_pk_mul_f32 v[208:209], v[112:113], v[112:113]
	v_pk_mul_f32 v[210:211], v[114:115], v[114:115]
	v_add_f32_e32 v233, v208, v209
	v_add_f32_e32 v233, v233, v210
	v_cvt_pk_bf16_f32 v224, v234, v235
	v_add_f32_e32 v233, v233, v211
	v_add_f32_e32 v232, v232, v233
	v_pk_mul_f32 v[234:235], v[110:111], v[214:215]
	s_nop 0
	v_cvt_pk_bf16_f32 v227, v234, v235
	v_pk_mul_f32 v[234:235], v[108:109], v[212:213]
	v_pk_mul_f32 v[212:213], v[108:109], v[108:109]
	v_pk_mul_f32 v[214:215], v[110:111], v[110:111]
	v_add_f32_e32 v233, v212, v213
	v_add_f32_e32 v233, v233, v214
	v_cvt_pk_bf16_f32 v226, v234, v235
	v_add_f32_e32 v233, v233, v215
	v_add_f32_e32 v232, v232, v233
	s_nop 1
	v_permlane16_swap_b32_e32 v224, v226
	v_permlane16_swap_b32_e32 v225, v227
	v_pk_mul_f32 v[234:235], v[106:107], v[218:219]
	s_nop 0
	v_cvt_pk_bf16_f32 v229, v234, v235
	v_pk_mul_f32 v[234:235], v[104:105], v[216:217]
	v_pk_mul_f32 v[216:217], v[104:105], v[104:105]
	v_pk_mul_f32 v[218:219], v[106:107], v[106:107]
	v_add_f32_e32 v233, v216, v217
	v_add_f32_e32 v233, v233, v218
	v_cvt_pk_bf16_f32 v228, v234, v235
	v_add_f32_e32 v233, v233, v219
	v_add_f32_e32 v232, v232, v233
	v_pk_mul_f32 v[234:235], v[102:103], v[222:223]
	s_nop 0
	v_cvt_pk_bf16_f32 v231, v234, v235
	v_pk_mul_f32 v[234:235], v[100:101], v[220:221]
	v_pk_mul_f32 v[220:221], v[100:101], v[100:101]
	v_pk_mul_f32 v[222:223], v[102:103], v[102:103]
	v_add_f32_e32 v233, v220, v221
	v_add_f32_e32 v233, v233, v222
	v_cvt_pk_bf16_f32 v230, v234, v235
	v_add_f32_e32 v233, v233, v223
	v_add_f32_e32 v232, v232, v233
	s_nop 1
	v_permlane16_swap_b32_e32 v228, v230
	v_permlane16_swap_b32_e32 v229, v231
	v_mov_b32_e32 v192, v228
	v_mov_b32_e32 v193, v229
	v_mov_b32_e32 v194, v230
	v_mov_b32_e32 v195, v231
	v_mov_b32_dpp v228, v224 row_ror:8 row_mask:0xf bank_mask:0x3
	v_mov_b32_dpp v229, v225 row_ror:8 row_mask:0xf bank_mask:0x3
	v_mov_b32_dpp v230, v226 row_ror:8 row_mask:0xf bank_mask:0x3
	v_mov_b32_dpp v231, v227 row_ror:8 row_mask:0xf bank_mask:0x3
	v_mov_b32_dpp v224, v192 row_ror:8 row_mask:0xf bank_mask:0xc
	v_mov_b32_dpp v225, v193 row_ror:8 row_mask:0xf bank_mask:0xc
	v_mov_b32_dpp v226, v194 row_ror:8 row_mask:0xf bank_mask:0xc
	v_mov_b32_dpp v227, v195 row_ror:8 row_mask:0xf bank_mask:0xc
	global_store_dwordx4 v[188:189], v[224:227], off offset:288
	global_store_dwordx4 v[190:191], v[228:231], off offset:288
	s_nop 1
.Lmy_res_now_0_1:
	s_and_b64 vcc, exec, s[42:43]
	s_cbranch_vccz .Lmy_res_noat_0
	ds_bpermute_b32 v233, v171, v232
	s_waitcnt lgkmcnt(0)
	v_add_f32_e32 v232, v232, v233
	ds_bpermute_b32 v233, v172, v232
	s_waitcnt lgkmcnt(0)
	v_add_f32_e32 v232, v232, v233
	s_mov_b64 exec, s[12:13]
	global_atomic_add_f32 v[246:247], v232, off offset:0
	s_mov_b64 exec, -1
; __device__ __forceinline__ void gemm_phase(const Ctx& cx, const GemmArgs& g_, char* shm) {
;     ...
;             } else if (g.epi == EPI_RES) {
;               const float4 hv = *(const float4*)(g.hin + (size_t)tok * DM + n0);
;               const float h0 = hv.x + a[0], h1 = hv.y + a[1], h2 = hv.z + a[2], h3 = hv.w + a[3];
;               *(float4*)(g.hout + (size_t)tok * DM + n0) = make_float4(h0, h1, h2, h3);
;               if (g.w != nullptr) {
;                 const float4 nw = *(const float4*)(g.w + n0);
;                 uint2 o; o.x = pack2(h0 * nw.x, h1 * nw.y); o.y = pack2(h2 * nw.z, h3 * nw.w);
;                 EMIT_BF16(DM, o);
;                 ssq += h0 * h0 + h1 * h1 + h2 * h2 + h3 * h3;
;               }
.Lmy_res_noat_0:
	v_lshl_add_u64 v[188:189], v[184:185], 0, s[8:9]
	v_lshl_add_u64 v[190:191], v[188:189], 0, s[6:7]
	v_lshl_add_u64 v[236:237], v[240:241], 0, s[2:3]
	v_lshl_add_u64 v[238:239], v[242:243], 0, s[2:3]
	v_mov_b32_e32 v232, 0
	global_load_dwordx4 v[192:195], v[236:237], off offset:0
	global_load_dwordx4 v[196:199], v[236:237], off offset:64
	global_load_dwordx4 v[200:203], v[236:237], off offset:128
	global_load_dwordx4 v[204:207], v[236:237], off offset:192
	s_and_b64 vcc, exec, s[42:43]
	s_cbranch_vccz .Lmy_res_now_ld_1_0
	global_load_dwordx4 v[208:211], v[244:245], off offset:0
	global_load_dwordx4 v[212:215], v[244:245], off offset:64
	global_load_dwordx4 v[216:219], v[244:245], off offset:128
	global_load_dwordx4 v[220:223], v[244:245], off offset:192
.Lmy_res_now_ld_1_0:
	s_waitcnt vmcnt(0)
	v_pk_add_f32 v[96:97], v[96:97], v[192:193]
	v_pk_add_f32 v[98:99], v[98:99], v[194:195]
	global_store_dwordx4 v[238:239], v[96:99], off offset:0
	v_pk_add_f32 v[92:93], v[92:93], v[196:197]
	v_pk_add_f32 v[94:95], v[94:95], v[198:199]
	global_store_dwordx4 v[238:239], v[92:95], off offset:64
	v_pk_add_f32 v[88:89], v[88:89], v[200:201]
	v_pk_add_f32 v[90:91], v[90:91], v[202:203]
	global_store_dwordx4 v[238:239], v[88:91], off offset:128
	v_pk_add_f32 v[84:85], v[84:85], v[204:205]
	v_pk_add_f32 v[86:87], v[86:87], v[206:207]
	global_store_dwordx4 v[238:239], v[84:87], off offset:192
	s_and_b64 vcc, exec, s[42:43]
	s_cbranch_vccz .Lmy_res_now_1_0
	v_pk_mul_f32 v[234:235], v[98:99], v[210:211]
	s_nop 0
	v_cvt_pk_bf16_f32 v225, v234, v235
	v_pk_mul_f32 v[234:235], v[96:97], v[208:209]
	v_pk_mul_f32 v[208:209], v[96:97], v[96:97]
	v_pk_mul_f32 v[210:211], v[98:99], v[98:99]
	v_add_f32_e32 v233, v208, v209
	v_add_f32_e32 v233, v233, v210
	v_cvt_pk_bf16_f32 v224, v234, v235
	v_add_f32_e32 v233, v233, v211
	v_add_f32_e32 v232, v232, v233
	v_pk_mul_f32 v[234:235], v[94:95], v[214:215]
	s_nop 0
	v_cvt_pk_bf16_f32 v227, v234, v235
	v_pk_mul_f32 v[234:235], v[92:93], v[212:213]
	v_pk_mul_f32 v[212:213], v[92:93], v[92:93]
	v_pk_mul_f32 v[214:215], v[94:95], v[94:95]
	v_add_f32_e32 v233, v212, v213
	v_add_f32_e32 v233, v233, v214
	v_cvt_pk_bf16_f32 v226, v234, v235
	v_add_f32_e32 v233, v233, v215
	v_add_f32_e32 v232, v232, v233
	s_nop 1
	v_permlane16_swap_b32_e32 v224, v226
	v_permlane16_swap_b32_e32 v225, v227
	v_pk_mul_f32 v[234:235], v[90:91], v[218:219]
	s_nop 0
	v_cvt_pk_bf16_f32 v229, v234, v235
	v_pk_mul_f32 v[234:235], v[88:89], v[216:217]
	v_pk_mul_f32 v[216:217], v[88:89], v[88:89]
	v_pk_mul_f32 v[218:219], v[90:91], v[90:91]
	v_add_f32_e32 v233, v216, v217
	v_add_f32_e32 v233, v233, v218
	v_cvt_pk_bf16_f32 v228, v234, v235
	v_add_f32_e32 v233, v233, v219
	v_add_f32_e32 v232, v232, v233
	v_pk_mul_f32 v[234:235], v[86:87], v[222:223]
	s_nop 0
	v_cvt_pk_bf16_f32 v231, v234, v235
	v_pk_mul_f32 v[234:235], v[84:85], v[220:221]
	v_pk_mul_f32 v[220:221], v[84:85], v[84:85]
	v_pk_mul_f32 v[222:223], v[86:87], v[86:87]
	v_add_f32_e32 v233, v220, v221
	v_add_f32_e32 v233, v233, v222
	v_cvt_pk_bf16_f32 v230, v234, v235
	v_add_f32_e32 v233, v233, v223
	v_add_f32_e32 v232, v232, v233
	s_nop 1
	v_permlane16_swap_b32_e32 v228, v230
	v_permlane16_swap_b32_e32 v229, v231
	v_mov_b32_e32 v192, v228
	v_mov_b32_e32 v193, v229
	v_mov_b32_e32 v194, v230
	v_mov_b32_e32 v195, v231
	v_mov_b32_dpp v228, v224 row_ror:8 row_mask:0xf bank_mask:0x3
	v_mov_b32_dpp v229, v225 row_ror:8 row_mask:0xf bank_mask:0x3
	v_mov_b32_dpp v230, v226 row_ror:8 row_mask:0xf bank_mask:0x3
	v_mov_b32_dpp v231, v227 row_ror:8 row_mask:0xf bank_mask:0x3
	v_mov_b32_dpp v224, v192 row_ror:8 row_mask:0xf bank_mask:0xc
	v_mov_b32_dpp v225, v193 row_ror:8 row_mask:0xf bank_mask:0xc
	v_mov_b32_dpp v226, v194 row_ror:8 row_mask:0xf bank_mask:0xc
	v_mov_b32_dpp v227, v195 row_ror:8 row_mask:0xf bank_mask:0xc
	global_store_dwordx4 v[188:189], v[224:227], off offset:32
	global_store_dwordx4 v[190:191], v[228:231], off offset:32
	s_nop 1

; __device__ __forceinline__ void gemm_phase(const Ctx& cx, const GemmArgs& g_, char* shm) {
;     ...
;             } else if (g.epi == EPI_RES) {
;               const float4 hv = *(const float4*)(g.hin + (size_t)tok * DM + n0);
;               const float h0 = hv.x + a[0], h1 = hv.y + a[1], h2 = hv.z + a[2], h3 = hv.w + a[3];
;               *(float4*)(g.hout + (size_t)tok * DM + n0) = make_float4(h0, h1, h2, h3);
;               if (g.w != nullptr) {
;                 const float4 nw = *(const float4*)(g.w + n0);
;                 uint2 o; o.x = pack2(h0 * nw.x, h1 * nw.y); o.y = pack2(h2 * nw.z, h3 * nw.w);
;                 EMIT_BF16(DM, o);
;                 ssq += h0 * h0 + h1 * h1 + h2 * h2 + h3 * h3;
;               }
;     ...
;         if (g.epi == EPI_RES && g.w != nullptr) {
;           float v2 = ssq;
;           v2 += shx(lane, v2, 16);
;           v2 += shx(lane, v2, 32);
;           if (fq == 0) __hip_atomic_fetch_add(g.f32buf + tok, v2, __ATOMIC_RELAXED, __HIP_MEMORY_SCOPE_AGENT);
;         }
.Lmy_res_now_ld_1_1:
	s_waitcnt vmcnt(0)
	v_pk_add_f32 v[80:81], v[80:81], v[192:193]
	v_pk_add_f32 v[82:83], v[82:83], v[194:195]
	global_store_dwordx4 v[238:239], v[80:83], off offset:512
	v_pk_add_f32 v[76:77], v[76:77], v[196:197]
	v_pk_add_f32 v[78:79], v[78:79], v[198:199]
	global_store_dwordx4 v[238:239], v[76:79], off offset:576
	v_pk_add_f32 v[72:73], v[72:73], v[200:201]
	v_pk_add_f32 v[74:75], v[74:75], v[202:203]
	global_store_dwordx4 v[238:239], v[72:75], off offset:640
	v_pk_add_f32 v[68:69], v[68:69], v[204:205]
	v_pk_add_f32 v[70:71], v[70:71], v[206:207]
	global_store_dwordx4 v[238:239], v[68:71], off offset:704
	s_and_b64 vcc, exec, s[42:43]
	s_cbranch_vccz .Lmy_res_now_1_1
	v_pk_mul_f32 v[234:235], v[82:83], v[210:211]
	s_nop 0
	v_cvt_pk_bf16_f32 v225, v234, v235
	v_pk_mul_f32 v[234:235], v[80:81], v[208:209]
	v_pk_mul_f32 v[208:209], v[80:81], v[80:81]
	v_pk_mul_f32 v[210:211], v[82:83], v[82:83]
	v_add_f32_e32 v233, v208, v209
	v_add_f32_e32 v233, v233, v210
	v_cvt_pk_bf16_f32 v224, v234, v235
	v_add_f32_e32 v233, v233, v211
	v_add_f32_e32 v232, v232, v233
	v_pk_mul_f32 v[234:235], v[78:79], v[214:215]
	s_nop 0
	v_cvt_pk_bf16_f32 v227, v234, v235
	v_pk_mul_f32 v[234:235], v[76:77], v[212:213]
	v_pk_mul_f32 v[212:213], v[76:77], v[76:77]
	v_pk_mul_f32 v[214:215], v[78:79], v[78:79]
	v_add_f32_e32 v233, v212, v213
	v_add_f32_e32 v233, v233, v214
	v_cvt_pk_bf16_f32 v226, v234, v235
	v_add_f32_e32 v233, v233, v215
	v_add_f32_e32 v232, v232, v233
	s_nop 1
	v_permlane16_swap_b32_e32 v224, v226
	v_permlane16_swap_b32_e32 v225, v227
	v_pk_mul_f32 v[234:235], v[74:75], v[218:219]
	s_nop 0
	v_cvt_pk_bf16_f32 v229, v234, v235
	v_pk_mul_f32 v[234:235], v[72:73], v[216:217]
	v_pk_mul_f32 v[216:217], v[72:73], v[72:73]
	v_pk_mul_f32 v[218:219], v[74:75], v[74:75]
	v_add_f32_e32 v233, v216, v217
	v_add_f32_e32 v233, v233, v218
	v_cvt_pk_bf16_f32 v228, v234, v235
	v_add_f32_e32 v233, v233, v219
	v_add_f32_e32 v232, v232, v233
	v_pk_mul_f32 v[234:235], v[70:71], v[222:223]
	s_nop 0
	v_cvt_pk_bf16_f32 v231, v234, v235
	v_pk_mul_f32 v[234:235], v[68:69], v[220:221]
	v_pk_mul_f32 v[220:221], v[68:69], v[68:69]
	v_pk_mul_f32 v[222:223], v[70:71], v[70:71]
	v_add_f32_e32 v233, v220, v221
	v_add_f32_e32 v233, v233, v222
	v_cvt_pk_bf16_f32 v230, v234, v235
	v_add_f32_e32 v233, v233, v223
	v_add_f32_e32 v232, v232, v233
	s_nop 1
	v_permlane16_swap_b32_e32 v228, v230
	v_permlane16_swap_b32_e32 v229, v231
	v_mov_b32_e32 v192, v228
	v_mov_b32_e32 v193, v229
	v_mov_b32_e32 v194, v230
	v_mov_b32_e32 v195, v231
	v_mov_b32_dpp v228, v224 row_ror:8 row_mask:0xf bank_mask:0x3
	v_mov_b32_dpp v229, v225 row_ror:8 row_mask:0xf bank_mask:0x3
	v_mov_b32_dpp v230, v226 row_ror:8 row_mask:0xf bank_mask:0x3
	v_mov_b32_dpp v231, v227 row_ror:8 row_mask:0xf bank_mask:0x3
	v_mov_b32_dpp v224, v192 row_ror:8 row_mask:0xf bank_mask:0xc
	v_mov_b32_dpp v225, v193 row_ror:8 row_mask:0xf bank_mask:0xc
	v_mov_b32_dpp v226, v194 row_ror:8 row_mask:0xf bank_mask:0xc
	v_mov_b32_dpp v227, v195 row_ror:8 row_mask:0xf bank_mask:0xc
	global_store_dwordx4 v[188:189], v[224:227], off offset:288
	global_store_dwordx4 v[190:191], v[228:231], off offset:288
	s_nop 1
.Lmy_res_now_1_1:
	s_and_b64 vcc, exec, s[42:43]
	s_cbranch_vccz .Lmy_res_noat_1
	ds_bpermute_b32 v233, v171, v232
	s_waitcnt lgkmcnt(0)
	v_add_f32_e32 v232, v232, v233
	ds_bpermute_b32 v233, v172, v232
	s_waitcnt lgkmcnt(0)
	v_add_f32_e32 v232, v232, v233
	s_mov_b64 exec, s[12:13]
	global_atomic_add_f32 v[246:247], v232, off offset:64
	s_mov_b64 exec, -1
; __device__ __forceinline__ void gemm_phase(const Ctx& cx, const GemmArgs& g_, char* shm) {
;     ...
;             } else if (g.epi == EPI_RES) {
;               const float4 hv = *(const float4*)(g.hin + (size_t)tok * DM + n0);
;               const float h0 = hv.x + a[0], h1 = hv.y + a[1], h2 = hv.z + a[2], h3 = hv.w + a[3];
;               *(float4*)(g.hout + (size_t)tok * DM + n0) = make_float4(h0, h1, h2, h3);
;               if (g.w != nullptr) {
;                 const float4 nw = *(const float4*)(g.w + n0);
;                 uint2 o; o.x = pack2(h0 * nw.x, h1 * nw.y); o.y = pack2(h2 * nw.z, h3 * nw.w);
;                 EMIT_BF16(DM, o);
;                 ssq += h0 * h0 + h1 * h1 + h2 * h2 + h3 * h3;
;               }
.Lmy_res_noat_1:
	v_lshl_add_u64 v[188:189], v[184:185], 0, s[10:11]
	v_lshl_add_u64 v[190:191], v[188:189], 0, s[6:7]
	v_lshl_add_u64 v[236:237], v[240:241], 0, s[4:5]
	v_lshl_add_u64 v[238:239], v[242:243], 0, s[4:5]
	v_mov_b32_e32 v232, 0
	global_load_dwordx4 v[192:195], v[236:237], off offset:0
	global_load_dwordx4 v[196:199], v[236:237], off offset:64
	global_load_dwordx4 v[200:203], v[236:237], off offset:128
	global_load_dwordx4 v[204:207], v[236:237], off offset:192
	s_and_b64 vcc, exec, s[42:43]
	s_cbranch_vccz .Lmy_res_now_ld_2_0
	global_load_dwordx4 v[208:211], v[244:245], off offset:0
	global_load_dwordx4 v[212:215], v[244:245], off offset:64
	global_load_dwordx4 v[216:219], v[244:245], off offset:128
	global_load_dwordx4 v[220:223], v[244:245], off offset:192
.Lmy_res_now_ld_2_0:
	s_waitcnt vmcnt(0)
	v_pk_add_f32 v[64:65], v[64:65], v[192:193]
	v_pk_add_f32 v[66:67], v[66:67], v[194:195]
	global_store_dwordx4 v[238:239], v[64:67], off offset:0
	v_pk_add_f32 v[60:61], v[60:61], v[196:197]
	v_pk_add_f32 v[62:63], v[62:63], v[198:199]
	global_store_dwordx4 v[238:239], v[60:63], off offset:64
	v_pk_add_f32 v[56:57], v[56:57], v[200:201]
	v_pk_add_f32 v[58:59], v[58:59], v[202:203]
	global_store_dwordx4 v[238:239], v[56:59], off offset:128
	v_pk_add_f32 v[52:53], v[52:53], v[204:205]
	v_pk_add_f32 v[54:55], v[54:55], v[206:207]
	global_store_dwordx4 v[238:239], v[52:55], off offset:192
	s_and_b64 vcc, exec, s[42:43]
	s_cbranch_vccz .Lmy_res_now_2_0
	v_pk_mul_f32 v[234:235], v[66:67], v[210:211]
	s_nop 0
	v_cvt_pk_bf16_f32 v225, v234, v235
	v_pk_mul_f32 v[234:235], v[64:65], v[208:209]
	v_pk_mul_f32 v[208:209], v[64:65], v[64:65]
	v_pk_mul_f32 v[210:211], v[66:67], v[66:67]
	v_add_f32_e32 v233, v208, v209
	v_add_f32_e32 v233, v233, v210
	v_cvt_pk_bf16_f32 v224, v234, v235
	v_add_f32_e32 v233, v233, v211
	v_add_f32_e32 v232, v232, v233
	v_pk_mul_f32 v[234:235], v[62:63], v[214:215]
	s_nop 0
	v_cvt_pk_bf16_f32 v227, v234, v235
	v_pk_mul_f32 v[234:235], v[60:61], v[212:213]
	v_pk_mul_f32 v[212:213], v[60:61], v[60:61]
	v_pk_mul_f32 v[214:215], v[62:63], v[62:63]
	v_add_f32_e32 v233, v212, v213
	v_add_f32_e32 v233, v233, v214
	v_cvt_pk_bf16_f32 v226, v234, v235
	v_add_f32_e32 v233, v233, v215
	v_add_f32_e32 v232, v232, v233
	s_nop 1
	v_permlane16_swap_b32_e32 v224, v226
	v_permlane16_swap_b32_e32 v225, v227
	v_pk_mul_f32 v[234:235], v[58:59], v[218:219]
	s_nop 0
	v_cvt_pk_bf16_f32 v229, v234, v235
	v_pk_mul_f32 v[234:235], v[56:57], v[216:217]
	v_pk_mul_f32 v[216:217], v[56:57], v[56:57]
	v_pk_mul_f32 v[218:219], v[58:59], v[58:59]
	v_add_f32_e32 v233, v216, v217
	v_add_f32_e32 v233, v233, v218
	v_cvt_pk_bf16_f32 v228, v234, v235
	v_add_f32_e32 v233, v233, v219
	v_add_f32_e32 v232, v232, v233
	v_pk_mul_f32 v[234:235], v[54:55], v[222:223]
	s_nop 0
	v_cvt_pk_bf16_f32 v231, v234, v235
	v_pk_mul_f32 v[234:235], v[52:53], v[220:221]
	v_pk_mul_f32 v[220:221], v[52:53], v[52:53]
	v_pk_mul_f32 v[222:223], v[54:55], v[54:55]
	v_add_f32_e32 v233, v220, v221
	v_add_f32_e32 v233, v233, v222
	v_cvt_pk_bf16_f32 v230, v234, v235
	v_add_f32_e32 v233, v233, v223
	v_add_f32_e32 v232, v232, v233
	s_nop 1
	v_permlane16_swap_b32_e32 v228, v230
	v_permlane16_swap_b32_e32 v229, v231
	v_mov_b32_e32 v192, v228
	v_mov_b32_e32 v193, v229
	v_mov_b32_e32 v194, v230
	v_mov_b32_e32 v195, v231
	v_mov_b32_dpp v228, v224 row_ror:8 row_mask:0xf bank_mask:0x3
	v_mov_b32_dpp v229, v225 row_ror:8 row_mask:0xf bank_mask:0x3
	v_mov_b32_dpp v230, v226 row_ror:8 row_mask:0xf bank_mask:0x3
	v_mov_b32_dpp v231, v227 row_ror:8 row_mask:0xf bank_mask:0x3
	v_mov_b32_dpp v224, v192 row_ror:8 row_mask:0xf bank_mask:0xc
	v_mov_b32_dpp v225, v193 row_ror:8 row_mask:0xf bank_mask:0xc
	v_mov_b32_dpp v226, v194 row_ror:8 row_mask:0xf bank_mask:0xc
	v_mov_b32_dpp v227, v195 row_ror:8 row_mask:0xf bank_mask:0xc
	global_store_dwordx4 v[188:189], v[224:227], off offset:32
	global_store_dwordx4 v[190:191], v[228:231], off offset:32
	s_nop 1

; __device__ __forceinline__ void gemm_phase(const Ctx& cx, const GemmArgs& g_, char* shm) {
;     ...
;             } else if (g.epi == EPI_RES) {
;               const float4 hv = *(const float4*)(g.hin + (size_t)tok * DM + n0);
;               const float h0 = hv.x + a[0], h1 = hv.y + a[1], h2 = hv.z + a[2], h3 = hv.w + a[3];
;               *(float4*)(g.hout + (size_t)tok * DM + n0) = make_float4(h0, h1, h2, h3);
;               if (g.w != nullptr) {
;                 const float4 nw = *(const float4*)(g.w + n0);
;                 uint2 o; o.x = pack2(h0 * nw.x, h1 * nw.y); o.y = pack2(h2 * nw.z, h3 * nw.w);
;                 EMIT_BF16(DM, o);
;                 ssq += h0 * h0 + h1 * h1 + h2 * h2 + h3 * h3;
;               }
;     ...
;         if (g.epi == EPI_RES && g.w != nullptr) {
;           float v2 = ssq;
;           v2 += shx(lane, v2, 16);
;           v2 += shx(lane, v2, 32);
;           if (fq == 0) __hip_atomic_fetch_add(g.f32buf + tok, v2, __ATOMIC_RELAXED, __HIP_MEMORY_SCOPE_AGENT);
;         }
.Lmy_res_now_ld_2_1:
	s_waitcnt vmcnt(0)
	v_pk_add_f32 v[48:49], v[48:49], v[192:193]
	v_pk_add_f32 v[50:51], v[50:51], v[194:195]
	global_store_dwordx4 v[238:239], v[48:51], off offset:512
	v_pk_add_f32 v[44:45], v[44:45], v[196:197]
	v_pk_add_f32 v[46:47], v[46:47], v[198:199]
	global_store_dwordx4 v[238:239], v[44:47], off offset:576
	v_pk_add_f32 v[40:41], v[40:41], v[200:201]
	v_pk_add_f32 v[42:43], v[42:43], v[202:203]
	global_store_dwordx4 v[238:239], v[40:43], off offset:640
	v_pk_add_f32 v[36:37], v[36:37], v[204:205]
	v_pk_add_f32 v[38:39], v[38:39], v[206:207]
	global_store_dwordx4 v[238:239], v[36:39], off offset:704
	s_and_b64 vcc, exec, s[42:43]
	s_cbranch_vccz .Lmy_res_now_2_1
	v_pk_mul_f32 v[234:235], v[50:51], v[210:211]
	s_nop 0
	v_cvt_pk_bf16_f32 v225, v234, v235
	v_pk_mul_f32 v[234:235], v[48:49], v[208:209]
	v_pk_mul_f32 v[208:209], v[48:49], v[48:49]
	v_pk_mul_f32 v[210:211], v[50:51], v[50:51]
	v_add_f32_e32 v233, v208, v209
	v_add_f32_e32 v233, v233, v210
	v_cvt_pk_bf16_f32 v224, v234, v235
	v_add_f32_e32 v233, v233, v211
	v_add_f32_e32 v232, v232, v233
	v_pk_mul_f32 v[234:235], v[46:47], v[214:215]
	s_nop 0
	v_cvt_pk_bf16_f32 v227, v234, v235
	v_pk_mul_f32 v[234:235], v[44:45], v[212:213]
	v_pk_mul_f32 v[212:213], v[44:45], v[44:45]
	v_pk_mul_f32 v[214:215], v[46:47], v[46:47]
	v_add_f32_e32 v233, v212, v213
	v_add_f32_e32 v233, v233, v214
	v_cvt_pk_bf16_f32 v226, v234, v235
	v_add_f32_e32 v233, v233, v215
	v_add_f32_e32 v232, v232, v233
	s_nop 1
	v_permlane16_swap_b32_e32 v224, v226
	v_permlane16_swap_b32_e32 v225, v227
	v_pk_mul_f32 v[234:235], v[42:43], v[218:219]
	s_nop 0
	v_cvt_pk_bf16_f32 v229, v234, v235
	v_pk_mul_f32 v[234:235], v[40:41], v[216:217]
	v_pk_mul_f32 v[216:217], v[40:41], v[40:41]
	v_pk_mul_f32 v[218:219], v[42:43], v[42:43]
	v_add_f32_e32 v233, v216, v217
	v_add_f32_e32 v233, v233, v218
	v_cvt_pk_bf16_f32 v228, v234, v235
	v_add_f32_e32 v233, v233, v219
	v_add_f32_e32 v232, v232, v233
	v_pk_mul_f32 v[234:235], v[38:39], v[222:223]
	s_nop 0
	v_cvt_pk_bf16_f32 v231, v234, v235
	v_pk_mul_f32 v[234:235], v[36:37], v[220:221]
	v_pk_mul_f32 v[220:221], v[36:37], v[36:37]
	v_pk_mul_f32 v[222:223], v[38:39], v[38:39]
	v_add_f32_e32 v233, v220, v221
	v_add_f32_e32 v233, v233, v222
	v_cvt_pk_bf16_f32 v230, v234, v235
	v_add_f32_e32 v233, v233, v223
	v_add_f32_e32 v232, v232, v233
	s_nop 1
	v_permlane16_swap_b32_e32 v228, v230
	v_permlane16_swap_b32_e32 v229, v231
	v_mov_b32_e32 v192, v228
	v_mov_b32_e32 v193, v229
	v_mov_b32_e32 v194, v230
	v_mov_b32_e32 v195, v231
	v_mov_b32_dpp v228, v224 row_ror:8 row_mask:0xf bank_mask:0x3
	v_mov_b32_dpp v229, v225 row_ror:8 row_mask:0xf bank_mask:0x3
	v_mov_b32_dpp v230, v226 row_ror:8 row_mask:0xf bank_mask:0x3
	v_mov_b32_dpp v231, v227 row_ror:8 row_mask:0xf bank_mask:0x3
	v_mov_b32_dpp v224, v192 row_ror:8 row_mask:0xf bank_mask:0xc
	v_mov_b32_dpp v225, v193 row_ror:8 row_mask:0xf bank_mask:0xc
	v_mov_b32_dpp v226, v194 row_ror:8 row_mask:0xf bank_mask:0xc
	v_mov_b32_dpp v227, v195 row_ror:8 row_mask:0xf bank_mask:0xc
	global_store_dwordx4 v[188:189], v[224:227], off offset:288
	global_store_dwordx4 v[190:191], v[228:231], off offset:288
	s_nop 1
.Lmy_res_now_2_1:
	s_and_b64 vcc, exec, s[42:43]
	s_cbranch_vccz .Lmy_res_noat_2
	ds_bpermute_b32 v233, v171, v232
	s_waitcnt lgkmcnt(0)
	v_add_f32_e32 v232, v232, v233
	ds_bpermute_b32 v233, v172, v232
	s_waitcnt lgkmcnt(0)
	v_add_f32_e32 v232, v232, v233
	s_mov_b64 exec, s[12:13]
	global_atomic_add_f32 v[246:247], v232, off offset:512
	s_mov_b64 exec, -1
; __device__ __forceinline__ void gemm_phase(const Ctx& cx, const GemmArgs& g_, char* shm) {
;     ...
;             } else if (g.epi == EPI_RES) {
;               const float4 hv = *(const float4*)(g.hin + (size_t)tok * DM + n0);
;               const float h0 = hv.x + a[0], h1 = hv.y + a[1], h2 = hv.z + a[2], h3 = hv.w + a[3];
;               *(float4*)(g.hout + (size_t)tok * DM + n0) = make_float4(h0, h1, h2, h3);
;               if (g.w != nullptr) {
;                 const float4 nw = *(const float4*)(g.w + n0);
;                 uint2 o; o.x = pack2(h0 * nw.x, h1 * nw.y); o.y = pack2(h2 * nw.z, h3 * nw.w);
;                 EMIT_BF16(DM, o);
;                 ssq += h0 * h0 + h1 * h1 + h2 * h2 + h3 * h3;
;               }
.Lmy_res_noat_2:
	v_lshl_add_u64 v[188:189], v[184:185], 0, s[10:11]
	v_lshl_add_u64 v[188:189], v[188:189], 0, s[8:9]
	v_lshl_add_u64 v[190:191], v[188:189], 0, s[6:7]
	v_lshl_add_u64 v[236:237], v[240:241], 0, s[4:5]
	v_lshl_add_u64 v[236:237], v[236:237], 0, s[2:3]
	v_lshl_add_u64 v[238:239], v[242:243], 0, s[4:5]
	v_lshl_add_u64 v[238:239], v[238:239], 0, s[2:3]
	v_mov_b32_e32 v232, 0
	global_load_dwordx4 v[192:195], v[236:237], off offset:0
	global_load_dwordx4 v[196:199], v[236:237], off offset:64
	global_load_dwordx4 v[200:203], v[236:237], off offset:128
	global_load_dwordx4 v[204:207], v[236:237], off offset:192
	s_and_b64 vcc, exec, s[42:43]
	s_cbranch_vccz .Lmy_res_now_ld_3_0
	global_load_dwordx4 v[208:211], v[244:245], off offset:0
	global_load_dwordx4 v[212:215], v[244:245], off offset:64
	global_load_dwordx4 v[216:219], v[244:245], off offset:128
	global_load_dwordx4 v[220:223], v[244:245], off offset:192
.Lmy_res_now_ld_3_0:
	s_waitcnt vmcnt(0)
	v_pk_add_f32 v[32:33], v[32:33], v[192:193]
	v_pk_add_f32 v[34:35], v[34:35], v[194:195]
	global_store_dwordx4 v[238:239], v[32:35], off offset:0
	v_pk_add_f32 v[28:29], v[28:29], v[196:197]
	v_pk_add_f32 v[30:31], v[30:31], v[198:199]
	global_store_dwordx4 v[238:239], v[28:31], off offset:64
	v_pk_add_f32 v[24:25], v[24:25], v[200:201]
	v_pk_add_f32 v[26:27], v[26:27], v[202:203]
	global_store_dwordx4 v[238:239], v[24:27], off offset:128
	v_pk_add_f32 v[20:21], v[20:21], v[204:205]
	v_pk_add_f32 v[22:23], v[22:23], v[206:207]
	global_store_dwordx4 v[238:239], v[20:23], off offset:192
	s_and_b64 vcc, exec, s[42:43]
	s_cbranch_vccz .Lmy_res_now_3_0
	v_pk_mul_f32 v[234:235], v[34:35], v[210:211]
	s_nop 0
	v_cvt_pk_bf16_f32 v225, v234, v235
	v_pk_mul_f32 v[234:235], v[32:33], v[208:209]
	v_pk_mul_f32 v[208:209], v[32:33], v[32:33]
	v_pk_mul_f32 v[210:211], v[34:35], v[34:35]
	v_add_f32_e32 v233, v208, v209
	v_add_f32_e32 v233, v233, v210
	v_cvt_pk_bf16_f32 v224, v234, v235
	v_add_f32_e32 v233, v233, v211
	v_add_f32_e32 v232, v232, v233
	v_pk_mul_f32 v[234:235], v[30:31], v[214:215]
	s_nop 0
	v_cvt_pk_bf16_f32 v227, v234, v235
	v_pk_mul_f32 v[234:235], v[28:29], v[212:213]
	v_pk_mul_f32 v[212:213], v[28:29], v[28:29]
	v_pk_mul_f32 v[214:215], v[30:31], v[30:31]
	v_add_f32_e32 v233, v212, v213
	v_add_f32_e32 v233, v233, v214
	v_cvt_pk_bf16_f32 v226, v234, v235
	v_add_f32_e32 v233, v233, v215
	v_add_f32_e32 v232, v232, v233
	s_nop 1
	v_permlane16_swap_b32_e32 v224, v226
	v_permlane16_swap_b32_e32 v225, v227
	v_pk_mul_f32 v[234:235], v[26:27], v[218:219]
	s_nop 0
	v_cvt_pk_bf16_f32 v229, v234, v235
	v_pk_mul_f32 v[234:235], v[24:25], v[216:217]
	v_pk_mul_f32 v[216:217], v[24:25], v[24:25]
	v_pk_mul_f32 v[218:219], v[26:27], v[26:27]
	v_add_f32_e32 v233, v216, v217
	v_add_f32_e32 v233, v233, v218
	v_cvt_pk_bf16_f32 v228, v234, v235
	v_add_f32_e32 v233, v233, v219
	v_add_f32_e32 v232, v232, v233
	v_pk_mul_f32 v[234:235], v[22:23], v[222:223]
	s_nop 0
	v_cvt_pk_bf16_f32 v231, v234, v235
	v_pk_mul_f32 v[234:235], v[20:21], v[220:221]
	v_pk_mul_f32 v[220:221], v[20:21], v[20:21]
	v_pk_mul_f32 v[222:223], v[22:23], v[22:23]
	v_add_f32_e32 v233, v220, v221
	v_add_f32_e32 v233, v233, v222
	v_cvt_pk_bf16_f32 v230, v234, v235
	v_add_f32_e32 v233, v233, v223
	v_add_f32_e32 v232, v232, v233
	s_nop 1
	v_permlane16_swap_b32_e32 v228, v230
	v_permlane16_swap_b32_e32 v229, v231
	v_mov_b32_e32 v192, v228
	v_mov_b32_e32 v193, v229
	v_mov_b32_e32 v194, v230
	v_mov_b32_e32 v195, v231
	v_mov_b32_dpp v228, v224 row_ror:8 row_mask:0xf bank_mask:0x3
	v_mov_b32_dpp v229, v225 row_ror:8 row_mask:0xf bank_mask:0x3
	v_mov_b32_dpp v230, v226 row_ror:8 row_mask:0xf bank_mask:0x3
	v_mov_b32_dpp v231, v227 row_ror:8 row_mask:0xf bank_mask:0x3
	v_mov_b32_dpp v224, v192 row_ror:8 row_mask:0xf bank_mask:0xc
	v_mov_b32_dpp v225, v193 row_ror:8 row_mask:0xf bank_mask:0xc
	v_mov_b32_dpp v226, v194 row_ror:8 row_mask:0xf bank_mask:0xc
	v_mov_b32_dpp v227, v195 row_ror:8 row_mask:0xf bank_mask:0xc
	global_store_dwordx4 v[188:189], v[224:227], off offset:32
	global_store_dwordx4 v[190:191], v[228:231], off offset:32
	s_nop 1

; __device__ __forceinline__ void gemm_phase(const Ctx& cx, const GemmArgs& g_, char* shm) {
;     ...
;             } else if (g.epi == EPI_RES) {
;               const float4 hv = *(const float4*)(g.hin + (size_t)tok * DM + n0);
;               const float h0 = hv.x + a[0], h1 = hv.y + a[1], h2 = hv.z + a[2], h3 = hv.w + a[3];
;               *(float4*)(g.hout + (size_t)tok * DM + n0) = make_float4(h0, h1, h2, h3);
;               if (g.w != nullptr) {
;                 const float4 nw = *(const float4*)(g.w + n0);
;                 uint2 o; o.x = pack2(h0 * nw.x, h1 * nw.y); o.y = pack2(h2 * nw.z, h3 * nw.w);
;                 EMIT_BF16(DM, o);
;                 ssq += h0 * h0 + h1 * h1 + h2 * h2 + h3 * h3;
;               }
;     ...
;         if (g.epi == EPI_RES && g.w != nullptr) {
;           float v2 = ssq;
;           v2 += shx(lane, v2, 16);
;           v2 += shx(lane, v2, 32);
;           if (fq == 0) __hip_atomic_fetch_add(g.f32buf + tok, v2, __ATOMIC_RELAXED, __HIP_MEMORY_SCOPE_AGENT);
;         }
.Lmy_res_now_ld_3_1:
	s_waitcnt vmcnt(0)
	v_pk_add_f32 v[16:17], v[16:17], v[192:193]
	v_pk_add_f32 v[18:19], v[18:19], v[194:195]
	global_store_dwordx4 v[238:239], v[16:19], off offset:512
	v_pk_add_f32 v[12:13], v[12:13], v[196:197]
	v_pk_add_f32 v[14:15], v[14:15], v[198:199]
	global_store_dwordx4 v[238:239], v[12:15], off offset:576
	v_pk_add_f32 v[8:9], v[8:9], v[200:201]
	v_pk_add_f32 v[10:11], v[10:11], v[202:203]
	global_store_dwordx4 v[238:239], v[8:11], off offset:640
	v_pk_add_f32 v[4:5], v[4:5], v[204:205]
	v_pk_add_f32 v[6:7], v[6:7], v[206:207]
	global_store_dwordx4 v[238:239], v[4:7], off offset:704
	s_and_b64 vcc, exec, s[42:43]
	s_cbranch_vccz .Lmy_res_now_3_1
	v_pk_mul_f32 v[234:235], v[18:19], v[210:211]
	s_nop 0
	v_cvt_pk_bf16_f32 v225, v234, v235
	v_pk_mul_f32 v[234:235], v[16:17], v[208:209]
	v_pk_mul_f32 v[208:209], v[16:17], v[16:17]
	v_pk_mul_f32 v[210:211], v[18:19], v[18:19]
	v_add_f32_e32 v233, v208, v209
	v_add_f32_e32 v233, v233, v210
	v_cvt_pk_bf16_f32 v224, v234, v235
	v_add_f32_e32 v233, v233, v211
	v_add_f32_e32 v232, v232, v233
	v_pk_mul_f32 v[234:235], v[14:15], v[214:215]
	s_nop 0
	v_cvt_pk_bf16_f32 v227, v234, v235
	v_pk_mul_f32 v[234:235], v[12:13], v[212:213]
	v_pk_mul_f32 v[212:213], v[12:13], v[12:13]
	v_pk_mul_f32 v[214:215], v[14:15], v[14:15]
	v_add_f32_e32 v233, v212, v213
	v_add_f32_e32 v233, v233, v214
	v_cvt_pk_bf16_f32 v226, v234, v235
	v_add_f32_e32 v233, v233, v215
	v_add_f32_e32 v232, v232, v233
	s_nop 1
	v_permlane16_swap_b32_e32 v224, v226
	v_permlane16_swap_b32_e32 v225, v227
	v_pk_mul_f32 v[234:235], v[10:11], v[218:219]
	s_nop 0
	v_cvt_pk_bf16_f32 v229, v234, v235
	v_pk_mul_f32 v[234:235], v[8:9], v[216:217]
	v_pk_mul_f32 v[216:217], v[8:9], v[8:9]
	v_pk_mul_f32 v[218:219], v[10:11], v[10:11]
	v_add_f32_e32 v233, v216, v217
	v_add_f32_e32 v233, v233, v218
	v_cvt_pk_bf16_f32 v228, v234, v235
	v_add_f32_e32 v233, v233, v219
	v_add_f32_e32 v232, v232, v233
	v_pk_mul_f32 v[234:235], v[6:7], v[222:223]
	s_nop 0
	v_cvt_pk_bf16_f32 v231, v234, v235
	v_pk_mul_f32 v[234:235], v[4:5], v[220:221]
	v_pk_mul_f32 v[220:221], v[4:5], v[4:5]
	v_pk_mul_f32 v[222:223], v[6:7], v[6:7]
	v_add_f32_e32 v233, v220, v221
	v_add_f32_e32 v233, v233, v222
	v_cvt_pk_bf16_f32 v230, v234, v235
	v_add_f32_e32 v233, v233, v223
	v_add_f32_e32 v232, v232, v233
	s_nop 1
	v_permlane16_swap_b32_e32 v228, v230
	v_permlane16_swap_b32_e32 v229, v231
	v_mov_b32_e32 v192, v228
	v_mov_b32_e32 v193, v229
	v_mov_b32_e32 v194, v230
	v_mov_b32_e32 v195, v231
	v_mov_b32_dpp v228, v224 row_ror:8 row_mask:0xf bank_mask:0x3
	v_mov_b32_dpp v229, v225 row_ror:8 row_mask:0xf bank_mask:0x3
	v_mov_b32_dpp v230, v226 row_ror:8 row_mask:0xf bank_mask:0x3
	v_mov_b32_dpp v231, v227 row_ror:8 row_mask:0xf bank_mask:0x3
	v_mov_b32_dpp v224, v192 row_ror:8 row_mask:0xf bank_mask:0xc
	v_mov_b32_dpp v225, v193 row_ror:8 row_mask:0xf bank_mask:0xc
	v_mov_b32_dpp v226, v194 row_ror:8 row_mask:0xf bank_mask:0xc
	v_mov_b32_dpp v227, v195 row_ror:8 row_mask:0xf bank_mask:0xc
	global_store_dwordx4 v[188:189], v[224:227], off offset:288
	global_store_dwordx4 v[190:191], v[228:231], off offset:288
	s_nop 1
.Lmy_res_now_3_1:
	s_and_b64 vcc, exec, s[42:43]
	s_cbranch_vccz .Lmy_res_noat_3
	ds_bpermute_b32 v233, v171, v232
	s_waitcnt lgkmcnt(0)
	v_add_f32_e32 v232, v232, v233
	ds_bpermute_b32 v233, v172, v232
	s_waitcnt lgkmcnt(0)
	v_add_f32_e32 v232, v232, v233
	s_mov_b64 exec, s[12:13]
	global_atomic_add_f32 v[246:247], v232, off offset:576
	s_mov_b64 exec, -1
.Lmy_res_noat_3:
	s_branch .LBB0_231
.Lmy_slow_epi:
	v_or_b32_e32 v136, s4, v168
	v_ashrrev_i32_e32 v137, 31, v136
	v_cndmask_b32_e64 v2, 0, 1, s[40:41]
	v_mov_b32_e32 v154, 1.0
	v_cmp_ne_u32_e64 s[8:9], 1, v2
	s_andn2_b64 vcc, exec, s[40:41]
	v_lshl_add_u64 v[142:143], v[136:137], 2, s[22:23]
	s_cbranch_vccnz .LBB0_250
	flat_load_dword v2, v[142:143]
	s_waitcnt vmcnt(0) lgkmcnt(0)
	v_fmamk_f32 v2, v2, 0x3a000000, v163
	v_mul_f32_e32 v132, 0x4b800000, v2
	v_cmp_gt_f32_e32 vcc, s83, v2
	s_nop 1
	v_cndmask_b32_e32 v2, v2, v132, vcc
	v_rsq_f32_e32 v2, v2
	s_nop 0
	v_mul_f32_e32 v132, 0x45800000, v2
	v_cndmask_b32_e32 v154, v2, v132, vcc
